# global barriers: every workgroup issues an un-waited buffer_wbl2 on arrival so the L2 flush starts at the first arrival
# baseline (speedup 1.0000x reference)
.LBB0_81:
	s_mul_i32 s0, s95, s94
	s_mul_i32 s0, s0, s26
	v_writelane_b32 v242, s0, 17
	s_add_u32 s0, s92, 0x510200
	s_addc_u32 s1, s93, 0
	v_writelane_b32 v242, s0, 18
	s_waitcnt vmcnt(0)
	s_barrier
	s_nop 0
	v_writelane_b32 v242, s1, 19
	s_add_u32 s0, s92, 0x510400
	s_addc_u32 s1, s93, 0
	v_writelane_b32 v242, s0, 20
	s_nop 1
	v_writelane_b32 v242, s1, 21
	s_add_u32 s0, s92, 0x510500
	s_addc_u32 s1, s93, 0
	v_writelane_b32 v242, s0, 22
	s_nop 1
	v_writelane_b32 v242, s1, 23
	s_add_u32 s0, s92, 0x510600
	s_addc_u32 s1, s93, 0
	v_writelane_b32 v242, s0, 24
	s_nop 1
	v_writelane_b32 v242, s1, 25
	s_add_u32 s0, s92, 0x510700
	s_addc_u32 s1, s93, 0
	v_writelane_b32 v242, s0, 26
	s_nop 1
	v_writelane_b32 v242, s1, 27
	s_add_u32 s0, s92, 0x510800
	s_addc_u32 s1, s93, 0
	v_writelane_b32 v242, s0, 28
	s_nop 1
	v_writelane_b32 v242, s1, 29
	s_add_u32 s0, s92, 0x510900
	s_addc_u32 s1, s93, 0
	v_writelane_b32 v242, s0, 30
	s_nop 1
	v_writelane_b32 v242, s1, 31
	s_add_u32 s0, s92, 0x510a00
	s_addc_u32 s1, s93, 0
	v_writelane_b32 v242, s0, 32
	s_nop 1
	v_writelane_b32 v242, s1, 33
	s_add_u32 s0, s92, 0x510b00
	s_addc_u32 s1, s93, 0
	v_writelane_b32 v242, s0, 34
	s_nop 1
	v_writelane_b32 v242, s1, 35
	s_add_u32 s0, s92, 0x510c00
	s_addc_u32 s1, s93, 0
	v_writelane_b32 v242, s0, 36
	s_nop 1
	v_writelane_b32 v242, s1, 37
	s_add_u32 s0, s92, 0x510d00
	s_addc_u32 s1, s93, 0
	v_writelane_b32 v242, s0, 38
	s_nop 1
	v_writelane_b32 v242, s1, 39
	s_add_u32 s0, s92, 0x510e00
	s_addc_u32 s1, s93, 0
	v_writelane_b32 v242, s0, 40
	s_nop 1
	v_writelane_b32 v242, s1, 41
	s_add_u32 s0, s92, 0x510f00
	s_addc_u32 s1, s93, 0
	v_writelane_b32 v242, s0, 42
	s_nop 1
	v_writelane_b32 v242, s1, 43
	s_add_u32 s0, s92, 0x511000
	s_addc_u32 s1, s93, 0
	v_writelane_b32 v242, s0, 44
	s_nop 1
	v_writelane_b32 v242, s1, 45
	s_add_u32 s0, s92, 0x511100
	s_addc_u32 s1, s93, 0
	v_writelane_b32 v242, s0, 46
	s_nop 1
	v_writelane_b32 v242, s1, 47
	s_add_u32 s0, s92, 0x511200
	s_addc_u32 s1, s93, 0
	v_writelane_b32 v242, s0, 48
	s_nop 1
	v_writelane_b32 v242, s1, 49
	s_add_u32 s0, s92, 0x511300
	s_addc_u32 s1, s93, 0
	v_writelane_b32 v242, s0, 50
	s_cmp_eq_u32 s3, 15
	s_nop 0
	v_writelane_b32 v242, s1, 51
	s_cselect_b64 s[0:1], -1, 0
	v_writelane_b32 v242, s0, 52
	s_cmp_eq_u32 s3, 14
	s_nop 0
	v_writelane_b32 v242, s1, 53
	s_cselect_b64 s[0:1], -1, 0
	v_writelane_b32 v242, s0, 54
	s_cmp_eq_u32 s3, 13
	s_nop 0
	v_writelane_b32 v242, s1, 55
	s_cselect_b64 s[0:1], -1, 0
	v_writelane_b32 v242, s0, 56
	s_cmp_eq_u32 s3, 12
	s_nop 0
	v_writelane_b32 v242, s1, 57
	s_cselect_b64 s[0:1], -1, 0
	v_writelane_b32 v242, s0, 58
	s_cmp_eq_u32 s3, 11
	s_nop 0
	v_writelane_b32 v242, s1, 59
	s_cselect_b64 s[0:1], -1, 0
	v_writelane_b32 v242, s0, 60
	s_cmp_eq_u32 s3, 10
	s_nop 0
	v_writelane_b32 v242, s1, 61
	s_cselect_b64 s[0:1], -1, 0
	v_writelane_b32 v242, s0, 62
	s_cmp_eq_u32 s3, 9
	s_nop 0
	v_writelane_b32 v242, s1, 63
	s_cselect_b64 s[0:1], -1, 0
	v_writelane_b32 v240, s0, 0
	s_cmp_eq_u32 s3, 8
	v_readlane_b32 s49, v242, 9
	v_writelane_b32 v240, s1, 1
	s_cselect_b64 s[0:1], -1, 0
	v_writelane_b32 v240, s0, 2
	s_cmp_eq_u32 s3, 7
	s_nop 0
	v_writelane_b32 v240, s1, 3
	s_cselect_b64 s[0:1], -1, 0
	v_writelane_b32 v240, s0, 4
	s_cmp_eq_u32 s3, 6
	s_nop 0
	v_writelane_b32 v240, s1, 5
	s_cselect_b64 s[0:1], -1, 0
	v_writelane_b32 v240, s0, 6
	s_cmp_eq_u32 s3, 5
	s_nop 0
	v_writelane_b32 v240, s1, 7
	s_cselect_b64 s[0:1], -1, 0
	v_writelane_b32 v240, s0, 8
	s_cmp_eq_u32 s3, 4
	s_nop 0
	v_writelane_b32 v240, s1, 9
	s_cselect_b64 s[0:1], -1, 0
	v_writelane_b32 v240, s0, 10
	s_cmp_eq_u32 s3, 3
	s_nop 0
	v_writelane_b32 v240, s1, 11
	s_cselect_b64 s[0:1], -1, 0
	v_writelane_b32 v240, s0, 12
	s_cmp_eq_u32 s3, 2
	s_nop 0
	v_writelane_b32 v240, s1, 13
	s_cselect_b64 s[0:1], -1, 0
	v_writelane_b32 v240, s0, 14
	s_cmp_eq_u32 s3, 1
	s_nop 0
	v_writelane_b32 v240, s1, 15
	s_cselect_b64 s[0:1], -1, 0
	v_writelane_b32 v240, s0, 16
	s_cmp_eq_u32 s3, 0
	s_nop 0
	v_writelane_b32 v240, s1, 17
	s_cselect_b64 s[0:1], -1, 0
	v_writelane_b32 v240, s0, 18
	s_nop 1
	v_writelane_b32 v240, s1, 19
	s_lshl_b32 s0, s3, 8
	s_add_u32 s0, s14, s0
	s_addc_u32 s1, s15, 0
	s_add_u32 s4, s0, 0x1400
	s_addc_u32 s5, s1, 0
	v_writelane_b32 v240, s4, 20
	s_add_u32 s0, s0, 0x2400
	s_addc_u32 s1, s1, 0
	v_writelane_b32 v240, s5, 21
	v_writelane_b32 v240, s0, 22
	s_nop 1
	v_writelane_b32 v240, s1, 23
	s_add_u32 s0, s92, 0x513400
	s_addc_u32 s1, s93, 0
	v_writelane_b32 v240, s0, 24
	s_nop 1
	v_writelane_b32 v240, s1, 25
	s_add_u32 s0, s92, 0x513500
	s_addc_u32 s1, s93, 0
	v_writelane_b32 v240, s0, 26
	s_nop 1
	v_writelane_b32 v240, s1, 27
	v_readfirstlane_b32 s0, v194
	s_cmp_gt_u32 s0, 63
	s_cbranch_scc1 .LBB0_135
	v_mbcnt_lo_u32_b32 v0, -1, 0
	v_mbcnt_hi_u32_b32 v0, -1, v0
	s_nop 0
	v_cmp_eq_u32_e32 vcc, 0, v0
	s_and_saveexec_b64 s[0:1], vcc
	s_cbranch_execz .LBB0_134
	buffer_wbl2 sc1
	s_add_i32 s3, 0, 0x23ff0
	v_mov_b32_e32 v0, s3
	s_waitcnt vmcnt(0) expcnt(0) lgkmcnt(0)
	ds_read_b32 v2, v0
	s_add_i32 s3, 0, 0x23ff4
	v_mov_b32_e32 v0, s3
	ds_read_b32 v0, v0
	s_waitcnt lgkmcnt(1)
	v_cmp_ne_u32_e32 vcc, 0, v2
	s_cbranch_vccnz .LBB0_98
	s_mov_b32 s3, 1
	v_mov_b32_e32 v16, 0
	s_branch .LBB0_86

.Lscan_loop:
	s_and_b32 s7, s6, 3
	s_lshl_b32 s7, s7, 12
	v_add_u32_e32 v23, s7, v22
	ds_read_b128 v[32:35], v10 offset:0
	ds_read_b128 v[48:51], v11 offset:0
	ds_read_b128 v[36:39], v10 offset:64
	ds_read_b128 v[52:55], v12 offset:0
	ds_read_b128 v[40:43], v10 offset:128
	ds_read_b128 v[56:59], v13 offset:0
	ds_read_b128 v[44:47], v10 offset:192
	ds_read_b128 v[60:63], v14 offset:0
	ds_read_u16 v80, v23 offset:0
	ds_read_u16 v81, v23 offset:64
	ds_read_u16 v82, v23 offset:128
	ds_read_u16 v83, v23 offset:192
	s_add_u32 s33, s6, 1
	s_min_u32 s33, s33, 31
	s_add_u32 s36, s6, 2
	s_min_u32 s36, s36, 31
	v_readlane_b32 s37, v24, s6
	s_nop 1
	v_mul_f32_e32 v92, s37, v92
	v_mul_f32_e32 v93, s37, v93
	v_mul_f32_e32 v94, s37, v94
	v_mul_f32_e32 v95, s37, v95
	v_mul_f32_e32 v96, s37, v96
	v_mul_f32_e32 v97, s37, v97
	v_mul_f32_e32 v98, s37, v98
	v_mul_f32_e32 v99, s37, v99
	s_waitcnt lgkmcnt(10)
	v_mfma_f32_16x16x32_bf16 v[84:87], v[48:51], v[32:35], 0
	s_waitcnt lgkmcnt(8)
	v_mfma_f32_16x16x32_bf16 v[84:87], v[52:55], v[36:39], v[84:87]
	s_waitcnt lgkmcnt(6)
	v_mfma_f32_16x16x32_bf16 v[84:87], v[56:59], v[40:43], v[84:87]
	s_waitcnt lgkmcnt(4)
	v_mfma_f32_16x16x32_bf16 v[84:87], v[60:63], v[44:47], v[84:87]
	ds_read_b128 v[64:67], v11 offset:32768
	ds_read_b128 v[68:71], v12 offset:32768
	ds_read_b128 v[72:75], v13 offset:32768
	ds_read_b128 v[76:79], v14 offset:32768
	s_waitcnt lgkmcnt(4)
	v_lshlrev_b32_e32 v80, 16, v80
	v_lshlrev_b32_e32 v81, 16, v81
	v_lshlrev_b32_e32 v82, 16, v82
	v_lshlrev_b32_e32 v83, 16, v83
	v_sub_f32_e32 v26, v80, v84
	v_sub_f32_e32 v27, v81, v85
	v_sub_f32_e32 v28, v82, v86
	v_sub_f32_e32 v29, v83, v87
	v_cvt_pk_bf16_f32 v26, v26, v27
	v_cvt_pk_bf16_f32 v27, v28, v29
	ds_write_b64 v20, v[26:27]
	s_lshl_b32 s7, s33, 14
	s_add_u32 s26, s14, s7
	s_addc_u32 s27, s15, 0
	s_add_i32 m0, s30, 0x14000
	s_nop 0
	global_load_lds_dwordx4 v5, s[26:27]
	s_add_i32 m0, s30, 0x14400
	s_nop 0
	global_load_lds_dwordx4 v6, s[26:27]
	s_lshl_b32 s7, s33, 13
	s_add_u32 s28, s18, s7
	s_addc_u32 s29, s19, 0
	s_add_i32 m0, s31, 0x1a000
	s_nop 0
	global_load_lds_dwordx4 v7, s[28:29]
	s_lshl_b32 s7, s36, 14
	s_add_u32 s26, s24, s7
	s_addc_u32 s27, s25, 0
	s_add_u32 s8, s6, 2
	s_and_b32 s8, s8, 3
	s_lshl_b32 s8, s8, 12
	s_add_u32 s8, s8, s32
	s_add_i32 m0, s8, 0x1f400
	s_nop 0
	global_load_lds_dwordx4 v8, s[26:27]
	s_waitcnt vmcnt(10) lgkmcnt(0)
	s_barrier
	ds_read_b128 v[100:103], v19
	ds_read_b128 v[108:111], v15 offset:0
	ds_read_b128 v[112:115], v15 offset:2048
	ds_read_b128 v[104:107], v19 offset:64
	ds_read_b128 v[116:119], v16 offset:0
	ds_read_b128 v[120:123], v16 offset:2048
	ds_read_b128 v[124:127], v17 offset:0
	ds_read_b128 v[128:131], v18 offset:0
	v_mfma_f32_16x16x32_bf16 v[88:91], v[32:35], v[64:67], 0
	v_mfma_f32_16x16x32_bf16 v[88:91], v[36:39], v[68:71], v[88:91]
	v_mfma_f32_16x16x32_bf16 v[88:91], v[40:43], v[72:75], v[88:91]
	v_mfma_f32_16x16x32_bf16 v[88:91], v[44:47], v[76:79], v[88:91]
	s_waitcnt lgkmcnt(6)
	v_mfma_f32_16x16x32_bf16 v[92:95], v[108:111], v[100:103], v[92:95]
	s_waitcnt lgkmcnt(5)
	v_mfma_f32_16x16x32_bf16 v[96:99], v[112:115], v[100:103], v[96:99]
	s_waitcnt lgkmcnt(3)
	v_mfma_f32_16x16x32_bf16 v[92:95], v[116:119], v[104:107], v[92:95]
	s_waitcnt lgkmcnt(2)
	v_mfma_f32_16x16x32_bf16 v[96:99], v[120:123], v[104:107], v[96:99]
	s_waitcnt lgkmcnt(1)
	v_mfma_f32_16x16x32_bf16 v[88:91], v[100:103], v[124:127], v[88:91]
	s_waitcnt lgkmcnt(0)
	v_mfma_f32_16x16x32_bf16 v[88:91], v[104:107], v[128:131], v[88:91]
	s_lshl_b32 s7, s6, 14
	s_add_u32 s28, s24, s7
	s_addc_u32 s29, s25, 0
	s_nop 1
	v_cvt_pk_bf16_f32 v26, v92, v93
	v_cvt_pk_bf16_f32 v27, v94, v95
	v_cvt_pk_bf16_f32 v28, v96, v97
	v_cvt_pk_bf16_f32 v29, v98, v99
	ds_write_b64 v21, v[26:27]
	ds_write_b64 v21, v[28:29] offset:32
	s_lshl_b32 s7, s36, 14
	s_add_u32 s26, s10, s7
	s_addc_u32 s27, s11, 0
	s_add_i32 m0, s30, 0x0
	s_nop 0
	global_load_lds_dwordx4 v3, s[26:27]
	s_add_i32 m0, s30, 0x400
	s_nop 0
	global_load_lds_dwordx4 v4, s[26:27]
	s_lshl_b32 s7, s36, 14
	s_add_u32 s26, s12, s7
	s_addc_u32 s27, s13, 0
	s_add_i32 m0, s30, 0x8000
	s_nop 0
	global_load_lds_dwordx4 v3, s[26:27]
	s_add_i32 m0, s30, 0x8400
	s_nop 0
	global_load_lds_dwordx4 v4, s[26:27]
	v_cvt_pk_bf16_f32 v80, v88, v89
	v_cvt_pk_bf16_f32 v81, v90, v91
	global_store_dwordx2 v9, v[80:81], s[28:29]
	s_add_u32 s6, s6, 1
	s_waitcnt vmcnt(10) lgkmcnt(0)
	s_barrier
	s_and_b32 s7, s6, 3
	s_lshl_b32 s7, s7, 12
	v_add_u32_e32 v23, s7, v22
	ds_read_b128 v[32:35], v10 offset:0
	ds_read_b128 v[48:51], v11 offset:16384
	ds_read_b128 v[36:39], v10 offset:64
	ds_read_b128 v[52:55], v12 offset:16384
	ds_read_b128 v[40:43], v10 offset:128
	ds_read_b128 v[56:59], v13 offset:16384
	ds_read_b128 v[44:47], v10 offset:192
	ds_read_b128 v[60:63], v14 offset:16384
	ds_read_u16 v80, v23 offset:0
	ds_read_u16 v81, v23 offset:64
	ds_read_u16 v82, v23 offset:128
	ds_read_u16 v83, v23 offset:192
	s_add_u32 s33, s6, 1
	s_min_u32 s33, s33, 31
	s_add_u32 s36, s6, 2
	s_min_u32 s36, s36, 31
	v_readlane_b32 s37, v24, s6
	s_nop 1
	v_mul_f32_e32 v92, s37, v92
	v_mul_f32_e32 v93, s37, v93
	v_mul_f32_e32 v94, s37, v94
	v_mul_f32_e32 v95, s37, v95
	v_mul_f32_e32 v96, s37, v96
	v_mul_f32_e32 v97, s37, v97
	v_mul_f32_e32 v98, s37, v98
	v_mul_f32_e32 v99, s37, v99
	s_waitcnt lgkmcnt(10)
	v_mfma_f32_16x16x32_bf16 v[84:87], v[48:51], v[32:35], 0
	s_waitcnt lgkmcnt(8)
	v_mfma_f32_16x16x32_bf16 v[84:87], v[52:55], v[36:39], v[84:87]
	s_waitcnt lgkmcnt(6)
	v_mfma_f32_16x16x32_bf16 v[84:87], v[56:59], v[40:43], v[84:87]
	s_waitcnt lgkmcnt(4)
	v_mfma_f32_16x16x32_bf16 v[84:87], v[60:63], v[44:47], v[84:87]
	ds_read_b128 v[64:67], v11 offset:49152
	ds_read_b128 v[68:71], v12 offset:49152
	ds_read_b128 v[72:75], v13 offset:49152
	ds_read_b128 v[76:79], v14 offset:49152
	s_waitcnt lgkmcnt(4)
	v_lshlrev_b32_e32 v80, 16, v80
	v_lshlrev_b32_e32 v81, 16, v81
	v_lshlrev_b32_e32 v82, 16, v82
	v_lshlrev_b32_e32 v83, 16, v83
	v_sub_f32_e32 v26, v80, v84
	v_sub_f32_e32 v27, v81, v85
	v_sub_f32_e32 v28, v82, v86
	v_sub_f32_e32 v29, v83, v87
	v_cvt_pk_bf16_f32 v26, v26, v27
	v_cvt_pk_bf16_f32 v27, v28, v29
	ds_write_b64 v20, v[26:27]
	s_lshl_b32 s7, s33, 14
	s_add_u32 s26, s14, s7
	s_addc_u32 s27, s15, 0
	s_add_i32 m0, s30, 0x10000
	s_nop 0
	global_load_lds_dwordx4 v5, s[26:27]
	s_add_i32 m0, s30, 0x10400
	s_nop 0
	global_load_lds_dwordx4 v6, s[26:27]
	s_lshl_b32 s7, s33, 13
	s_add_u32 s28, s18, s7
	s_addc_u32 s29, s19, 0
	s_add_i32 m0, s31, 0x18000
	s_nop 0
	global_load_lds_dwordx4 v7, s[28:29]
	s_lshl_b32 s7, s36, 14
	s_add_u32 s26, s24, s7
	s_addc_u32 s27, s25, 0
	s_add_u32 s8, s6, 2
	s_and_b32 s8, s8, 3
	s_lshl_b32 s8, s8, 12
	s_add_u32 s8, s8, s32
	s_add_i32 m0, s8, 0x1f400
	s_nop 0
	global_load_lds_dwordx4 v8, s[26:27]
	s_waitcnt vmcnt(10) lgkmcnt(0)
	s_barrier
	ds_read_b128 v[100:103], v19
	ds_read_b128 v[108:111], v15 offset:16384
	ds_read_b128 v[112:115], v15 offset:18432
	ds_read_b128 v[104:107], v19 offset:64
	ds_read_b128 v[116:119], v16 offset:16384
	ds_read_b128 v[120:123], v16 offset:18432
	ds_read_b128 v[124:127], v17 offset:8192
	ds_read_b128 v[128:131], v18 offset:8192
	v_mfma_f32_16x16x32_bf16 v[88:91], v[32:35], v[64:67], 0
	v_mfma_f32_16x16x32_bf16 v[88:91], v[36:39], v[68:71], v[88:91]
	v_mfma_f32_16x16x32_bf16 v[88:91], v[40:43], v[72:75], v[88:91]
	v_mfma_f32_16x16x32_bf16 v[88:91], v[44:47], v[76:79], v[88:91]
	s_waitcnt lgkmcnt(6)
	v_mfma_f32_16x16x32_bf16 v[92:95], v[108:111], v[100:103], v[92:95]
	s_waitcnt lgkmcnt(5)
	v_mfma_f32_16x16x32_bf16 v[96:99], v[112:115], v[100:103], v[96:99]
	s_waitcnt lgkmcnt(3)
	v_mfma_f32_16x16x32_bf16 v[92:95], v[116:119], v[104:107], v[92:95]
	s_waitcnt lgkmcnt(2)
	v_mfma_f32_16x16x32_bf16 v[96:99], v[120:123], v[104:107], v[96:99]
	s_waitcnt lgkmcnt(1)
	v_mfma_f32_16x16x32_bf16 v[88:91], v[100:103], v[124:127], v[88:91]
	s_waitcnt lgkmcnt(0)
	v_mfma_f32_16x16x32_bf16 v[88:91], v[104:107], v[128:131], v[88:91]
	s_lshl_b32 s7, s6, 14
	s_add_u32 s28, s24, s7
	s_addc_u32 s29, s25, 0
	s_nop 1
	v_cvt_pk_bf16_f32 v26, v92, v93
	v_cvt_pk_bf16_f32 v27, v94, v95
	v_cvt_pk_bf16_f32 v28, v96, v97
	v_cvt_pk_bf16_f32 v29, v98, v99
	ds_write_b64 v21, v[26:27]
	ds_write_b64 v21, v[28:29] offset:32
	s_lshl_b32 s7, s36, 14
	s_add_u32 s26, s10, s7
	s_addc_u32 s27, s11, 0
	s_add_i32 m0, s30, 0x4000
	s_nop 0
	global_load_lds_dwordx4 v3, s[26:27]
	s_add_i32 m0, s30, 0x4400
	s_nop 0
	global_load_lds_dwordx4 v4, s[26:27]
	s_lshl_b32 s7, s36, 14
	s_add_u32 s26, s12, s7
	s_addc_u32 s27, s13, 0
	s_add_i32 m0, s30, 0xc000
	s_nop 0
	global_load_lds_dwordx4 v3, s[26:27]
	s_add_i32 m0, s30, 0xc400
	s_nop 0
	global_load_lds_dwordx4 v4, s[26:27]
	v_cvt_pk_bf16_f32 v80, v88, v89
	v_cvt_pk_bf16_f32 v81, v90, v91
	global_store_dwordx2 v9, v[80:81], s[28:29]
	s_add_u32 s6, s6, 1
	s_waitcnt vmcnt(10) lgkmcnt(0)
	s_barrier
	s_cmp_lt_u32 s6, 32
	s_cbranch_scc1 .Lscan_loop
	s_lshl_b32 s56, s77, 5
	s_and_b32 s57, s40, 3
	s_lshl_b32 s72, s40, 5
	s_waitcnt vmcnt(0)
	v_readfirstlane_b32 s3, v194
	s_cmp_gt_u32 s3, 63
	s_barrier
	s_cbranch_scc1 .LBB0_421
	s_waitcnt vmcnt(2)
	v_mbcnt_lo_u32_b32 v0, -1, 0
	v_mbcnt_hi_u32_b32 v0, -1, v0
	s_nop 0
	v_cmp_eq_u32_e32 vcc, 0, v0
	s_and_saveexec_b64 s[6:7], vcc
	s_cbranch_execz .LBB0_420
	buffer_wbl2 sc1
	s_add_i32 s3, 0, 0x23ff0
	v_mov_b32_e32 v0, s3
	s_waitcnt vmcnt(0) expcnt(0) lgkmcnt(0)
	ds_read_b32 v2, v0
	s_add_i32 s3, 0, 0x23ff4
	v_mov_b32_e32 v0, s3
	ds_read_b32 v0, v0
	s_waitcnt lgkmcnt(1)
	v_cmp_ne_u32_e32 vcc, 0, v2
	s_cbranch_vccnz .LBB0_384
	s_mov_b32 s3, 1
	v_mov_b32_e32 v16, 0
	s_branch .LBB0_372

.LBB0_597:
	s_waitcnt vmcnt(0)
	v_readfirstlane_b32 s0, v194
	v_readlane_b32 s88, v242, 20
	s_cmp_gt_u32 s0, 63
	v_readlane_b32 s89, v242, 21
	s_barrier
	s_cbranch_scc1 .LBB0_651
	v_mbcnt_lo_u32_b32 v0, -1, 0
	v_mbcnt_hi_u32_b32 v0, -1, v0
	s_nop 0
	v_cmp_eq_u32_e32 vcc, 0, v0
	s_and_saveexec_b64 s[0:1], vcc
	s_cbranch_execz .LBB0_650
	buffer_wbl2 sc1
	s_add_i32 s3, 0, 0x23ff0
	v_mov_b32_e32 v0, s3
	s_waitcnt vmcnt(0) expcnt(0) lgkmcnt(0)
	ds_read_b32 v2, v0
	s_add_i32 s3, 0, 0x23ff4
	v_mov_b32_e32 v0, s3
	ds_read_b32 v0, v0
	s_waitcnt lgkmcnt(1)
	v_cmp_ne_u32_e32 vcc, 0, v2
	s_cbranch_vccnz .LBB0_614
	s_mov_b32 s3, 1
	v_mov_b32_e32 v16, 0
	s_branch .LBB0_602
